# G1 epilogue stores with nt cache hint (full-line streaming writes do not pollute L2 where H/W tiles are reused)
# speedup vs baseline: 1.1941x; 1.0078x over previous
; __device__ __forceinline__ void gemm_core_big(const bf16_t* __restrict__ A, int lda, const bf16_t* __restrict__ Bt, int ldb,
;                                               int K, f32x4 (&acc)[8][4], char* smem) {
;     ...
;   u32x4 ra[8], rb[4];
; #pragma unroll
;   for (int i = 0; i < 8; ++i) ra[i] = *(const u32x4*)(ap + (size_t)(32 * i) * lda);
; #pragma unroll
;   for (int i = 0; i < 4; ++i) rb[i] = *(const u32x4*)(bp + (size_t)(32 * i) * ldb);
;   for (int kt = 0; kt < nk; ++kt) {
;     __syncthreads();
; #pragma unroll
;     for (int i = 0; i < 8; ++i) *(u32x4*)(wA + 32 * i * LDS_STRIDE) = ra[i];
; #pragma unroll
;     for (int i = 0; i < 4; ++i) *(u32x4*)(wB + 32 * i * LDS_STRIDE) = rb[i];
;     __syncthreads();
;     {
;       const int k1 = min(kt + 1, nk - 1) << 6;
; #pragma unroll
;       for (int i = 0; i < 8; ++i) ra[i] = *(const u32x4*)(ap + (size_t)(32 * i) * lda + k1);
; #pragma unroll
;       for (int i = 0; i < 4; ++i) rb[i] = *(const u32x4*)(bp + (size_t)(32 * i) * ldb + k1);
;     }
; #pragma unroll
;     for (int ks = 0; ks < 2; ++ks) {
;       const int fo = ks ? fo1 : fo0;
;       bf16x8 bfr[4];
; #pragma unroll
;       for (int j = 0; j < 4; ++j) bfr[j] = *(const bf16x8*)(cB + j * 16 * LDS_STRIDE + fo);
; #pragma unroll
;       for (int i = 0; i < 8; ++i) {
;         const bf16x8 af = *(const bf16x8*)(cA + i * 16 * LDS_STRIDE + fo);
; #pragma unroll
;         for (int j = 0; j < 4; ++j)
;           acc[i][j] = __builtin_amdgcn_mfma_f32_16x16x32_bf16(bfr[j], af, acc[i][j], 0, 0, 0);
;       }
;     }
;   }
.LBB0_711:
	s_setprio 0
	global_load_dwordx4 v[144:147], v224, s[30:31]
	global_load_dwordx4 v[148:151], v224, s[28:29]
	global_load_dwordx4 v[134:137], v225, s[28:29]
	global_load_dwordx4 v[152:155], v226, s[28:29]
	global_load_dwordx4 v[156:159], v227, s[28:29]
	global_load_dwordx4 v[160:163], v228, s[28:29]
	global_load_dwordx4 v[164:167], v229, s[28:29]
	global_load_dwordx4 v[168:171], v230, s[28:29]
	global_load_dwordx4 v[172:175], v231, s[28:29]
	global_load_dwordx4 v[188:191], v225, s[30:31]
	global_load_dwordx4 v[192:195], v226, s[30:31]
	global_load_dwordx4 v[196:199], v227, s[30:31]
	s_add_u32 s28, s28, 0x80
	s_addc_u32 s29, s29, 0
	s_add_u32 s30, s30, 0x80
	s_addc_u32 s31, s31, 0
	s_barrier
	s_add_i32 s26, s26, 1
	s_lshl_b32 s18, s13, 7
	s_cmp_lg_u32 s26, 17
	s_waitcnt vmcnt(10)
	ds_write_b128 v2, v[148:151]
	ds_write_b128 v2, v[144:147] offset:32768
	s_waitcnt vmcnt(9)
	ds_write_b128 v2, v[134:137] offset:4096
	s_waitcnt vmcnt(8)
	ds_write_b128 v2, v[152:155] offset:8192
	s_waitcnt vmcnt(7)
	ds_write_b128 v2, v[156:159] offset:12288
	s_waitcnt vmcnt(6)
	ds_write_b128 v2, v[160:163] offset:16384
	s_waitcnt vmcnt(5)
	ds_write_b128 v2, v[164:167] offset:20480
	s_waitcnt vmcnt(4)
	ds_write_b128 v2, v[168:171] offset:24576
	s_waitcnt vmcnt(3)
	ds_write_b128 v2, v[172:175] offset:28672
	s_waitcnt vmcnt(2)
	ds_write_b128 v2, v[188:191] offset:36864
	s_waitcnt vmcnt(1)
	ds_write_b128 v2, v[192:195] offset:40960
	s_waitcnt vmcnt(0)
	ds_write_b128 v2, v[196:199] offset:45056
	s_waitcnt lgkmcnt(0)
	s_barrier
	ds_read_b128 v[134:137], v140 offset:32768
	ds_read_b128 v[144:147], v140 offset:34816
	ds_read_b128 v[156:159], v140 offset:36864
	ds_read_b128 v[160:163], v140 offset:38912
	ds_read_b128 v[148:151], v141 offset:0
	ds_read_b128 v[152:155], v141 offset:2048
	ds_read_b128 v[216:219], v141 offset:4096
	ds_read_b128 v[220:223], v141 offset:6144
	s_setprio 1
	s_waitcnt lgkmcnt(3)
	v_mfma_f32_16x16x32_bf16 v[128:131], v[134:137], v[148:151], v[128:131]
	v_mfma_f32_16x16x32_bf16 v[124:127], v[144:147], v[148:151], v[124:127]
	v_mfma_f32_16x16x32_bf16 v[120:123], v[156:159], v[148:151], v[120:123]
	v_mfma_f32_16x16x32_bf16 v[116:119], v[160:163], v[148:151], v[116:119]
	s_waitcnt lgkmcnt(2)
	v_mfma_f32_16x16x32_bf16 v[112:115], v[134:137], v[152:155], v[112:115]
	v_mfma_f32_16x16x32_bf16 v[108:111], v[144:147], v[152:155], v[108:111]
	v_mfma_f32_16x16x32_bf16 v[104:107], v[156:159], v[152:155], v[104:107]
	v_mfma_f32_16x16x32_bf16 v[100:103], v[160:163], v[152:155], v[100:103]
	ds_read_b128 v[148:151], v141 offset:8192
	ds_read_b128 v[152:155], v141 offset:10240
	s_waitcnt lgkmcnt(3)
	v_mfma_f32_16x16x32_bf16 v[96:99], v[134:137], v[216:219], v[96:99]
	v_mfma_f32_16x16x32_bf16 v[92:95], v[144:147], v[216:219], v[92:95]
	v_mfma_f32_16x16x32_bf16 v[88:91], v[156:159], v[216:219], v[88:91]
	v_mfma_f32_16x16x32_bf16 v[84:87], v[160:163], v[216:219], v[84:87]
	s_waitcnt lgkmcnt(2)
	v_mfma_f32_16x16x32_bf16 v[80:83], v[134:137], v[220:223], v[80:83]
	v_mfma_f32_16x16x32_bf16 v[76:79], v[144:147], v[220:223], v[76:79]
	v_mfma_f32_16x16x32_bf16 v[72:75], v[156:159], v[220:223], v[72:75]
	v_mfma_f32_16x16x32_bf16 v[68:71], v[160:163], v[220:223], v[68:71]
	ds_read_b128 v[216:219], v141 offset:12288
	ds_read_b128 v[220:223], v141 offset:14336
	ds_read_b128 v[200:203], v142 offset:32768
	ds_read_b128 v[204:207], v142 offset:34816
	ds_read_b128 v[208:211], v142 offset:36864
	ds_read_b128 v[212:215], v142 offset:38912
	s_waitcnt lgkmcnt(7)
	v_mfma_f32_16x16x32_bf16 v[64:67], v[134:137], v[148:151], v[64:67]
	v_mfma_f32_16x16x32_bf16 v[60:63], v[144:147], v[148:151], v[60:63]
	v_mfma_f32_16x16x32_bf16 v[56:59], v[156:159], v[148:151], v[56:59]
	v_mfma_f32_16x16x32_bf16 v[52:55], v[160:163], v[148:151], v[52:55]
	s_waitcnt lgkmcnt(6)
	v_mfma_f32_16x16x32_bf16 v[48:51], v[134:137], v[152:155], v[48:51]
	v_mfma_f32_16x16x32_bf16 v[44:47], v[144:147], v[152:155], v[44:47]
	v_mfma_f32_16x16x32_bf16 v[40:43], v[156:159], v[152:155], v[40:43]
	v_mfma_f32_16x16x32_bf16 v[36:39], v[160:163], v[152:155], v[36:39]
	ds_read_b128 v[148:151], v143 offset:0
	ds_read_b128 v[152:155], v143 offset:2048
	s_waitcnt lgkmcnt(7)
	v_mfma_f32_16x16x32_bf16 v[32:35], v[134:137], v[216:219], v[32:35]
	v_mfma_f32_16x16x32_bf16 v[24:27], v[144:147], v[216:219], v[24:27]
	v_mfma_f32_16x16x32_bf16 v[20:23], v[156:159], v[216:219], v[20:23]
	v_mfma_f32_16x16x32_bf16 v[16:19], v[160:163], v[216:219], v[16:19]
	s_waitcnt lgkmcnt(6)
	v_mfma_f32_16x16x32_bf16 v[12:15], v[134:137], v[220:223], v[12:15]
	v_mfma_f32_16x16x32_bf16 v[8:11], v[144:147], v[220:223], v[8:11]
	v_mfma_f32_16x16x32_bf16 v[4:7], v[156:159], v[220:223], v[4:7]
	v_mfma_f32_16x16x32_bf16 v[28:31], v[160:163], v[220:223], v[28:31]
	ds_read_b128 v[216:219], v143 offset:4096
	ds_read_b128 v[220:223], v143 offset:6144
	s_waitcnt lgkmcnt(3)
	v_mfma_f32_16x16x32_bf16 v[128:131], v[200:203], v[148:151], v[128:131]
	v_mfma_f32_16x16x32_bf16 v[124:127], v[204:207], v[148:151], v[124:127]
	v_mfma_f32_16x16x32_bf16 v[120:123], v[208:211], v[148:151], v[120:123]
	v_mfma_f32_16x16x32_bf16 v[116:119], v[212:215], v[148:151], v[116:119]
	s_waitcnt lgkmcnt(2)
	v_mfma_f32_16x16x32_bf16 v[112:115], v[200:203], v[152:155], v[112:115]
	v_mfma_f32_16x16x32_bf16 v[108:111], v[204:207], v[152:155], v[108:111]
	v_mfma_f32_16x16x32_bf16 v[104:107], v[208:211], v[152:155], v[104:107]
	v_mfma_f32_16x16x32_bf16 v[100:103], v[212:215], v[152:155], v[100:103]
	ds_read_b128 v[148:151], v143 offset:8192
	ds_read_b128 v[152:155], v143 offset:10240
	s_waitcnt lgkmcnt(3)
; __device__ __forceinline__ unsigned pack2(float a, float b) { return (unsigned)f2bf(a) | ((unsigned)f2bf(b) << 16); }
; __device__ __forceinline__ void gemm_core_big(const bf16_t* __restrict__ A, int lda, const bf16_t* __restrict__ Bt, int ldb,
;                                               int K, f32x4 (&acc)[8][4], char* smem) {
;     ...
;     for (int ks = 0; ks < 2; ++ks) {
;       const int fo = ks ? fo1 : fo0;
;       bf16x8 bfr[4];
; #pragma unroll
;       for (int j = 0; j < 4; ++j) bfr[j] = *(const bf16x8*)(cB + j * 16 * LDS_STRIDE + fo);
; #pragma unroll
;       for (int i = 0; i < 8; ++i) {
;         const bf16x8 af = *(const bf16x8*)(cA + i * 16 * LDS_STRIDE + fo);
; #pragma unroll
;         for (int j = 0; j < 4; ++j)
;           acc[i][j] = __builtin_amdgcn_mfma_f32_16x16x32_bf16(bfr[j], af, acc[i][j], 0, 0, 0);
;       }
;     }
; __device__ __forceinline__ void phase_gemm_in(const Params& p, char* smem) {
;     ...
;     bf16_t* dst; int ldd, ncol0;
;     if (nt < PRE_W / 128) { dst = PRE; ldd = PRE_W; ncol0 = nt * 128; }
;     else { dst = POST; ldd = POST_W; ncol0 = (nt - PRE_W / 128) * 128; }
; #pragma unroll
;     for (int i = 0; i < 8; ++i) {
;       const int m = mt * 256 + wm * 128 + i * 16 + (lane & 15);
; #pragma unroll
;       for (int j = 0; j < 4; ++j) {
;         const int n = ncol0 + wn * 64 + j * 16 + (lane >> 4) * 4;
;         uint2 o;
;         o.x = pack2(acc[i][j][0], acc[i][j][1]);
;         o.y = pack2(acc[i][j][2], acc[i][j][3]);
;         *(uint2*)(dst + (size_t)m * ldd + n) = o;
;       }
;     }
	v_mfma_f32_16x16x32_bf16 v[96:99], v[200:203], v[216:219], v[96:99]
	v_mfma_f32_16x16x32_bf16 v[92:95], v[204:207], v[216:219], v[92:95]
	v_mfma_f32_16x16x32_bf16 v[88:91], v[208:211], v[216:219], v[88:91]
	v_mfma_f32_16x16x32_bf16 v[84:87], v[212:215], v[216:219], v[84:87]
	s_waitcnt lgkmcnt(2)
	v_mfma_f32_16x16x32_bf16 v[80:83], v[200:203], v[220:223], v[80:83]
	v_mfma_f32_16x16x32_bf16 v[76:79], v[204:207], v[220:223], v[76:79]
	v_mfma_f32_16x16x32_bf16 v[72:75], v[208:211], v[220:223], v[72:75]
	v_mfma_f32_16x16x32_bf16 v[68:71], v[212:215], v[220:223], v[68:71]
	ds_read_b128 v[216:219], v143 offset:12288
	ds_read_b128 v[220:223], v143 offset:14336
	s_waitcnt lgkmcnt(3)
	v_mfma_f32_16x16x32_bf16 v[64:67], v[200:203], v[148:151], v[64:67]
	v_mfma_f32_16x16x32_bf16 v[60:63], v[204:207], v[148:151], v[60:63]
	v_mfma_f32_16x16x32_bf16 v[56:59], v[208:211], v[148:151], v[56:59]
	v_mfma_f32_16x16x32_bf16 v[52:55], v[212:215], v[148:151], v[52:55]
	s_waitcnt lgkmcnt(2)
	v_mfma_f32_16x16x32_bf16 v[48:51], v[200:203], v[152:155], v[48:51]
	v_mfma_f32_16x16x32_bf16 v[44:47], v[204:207], v[152:155], v[44:47]
	v_mfma_f32_16x16x32_bf16 v[40:43], v[208:211], v[152:155], v[40:43]
	v_mfma_f32_16x16x32_bf16 v[36:39], v[212:215], v[152:155], v[36:39]
	s_waitcnt lgkmcnt(1)
	v_mfma_f32_16x16x32_bf16 v[32:35], v[200:203], v[216:219], v[32:35]
	v_mfma_f32_16x16x32_bf16 v[24:27], v[204:207], v[216:219], v[24:27]
	v_mfma_f32_16x16x32_bf16 v[20:23], v[208:211], v[216:219], v[20:23]
	v_mfma_f32_16x16x32_bf16 v[16:19], v[212:215], v[216:219], v[16:19]
	s_waitcnt lgkmcnt(0)
	v_mfma_f32_16x16x32_bf16 v[12:15], v[200:203], v[220:223], v[12:15]
	v_mfma_f32_16x16x32_bf16 v[8:11], v[204:207], v[220:223], v[8:11]
	v_mfma_f32_16x16x32_bf16 v[4:7], v[208:211], v[220:223], v[4:7]
	v_mfma_f32_16x16x32_bf16 v[28:31], v[212:215], v[220:223], v[28:31]
	s_cbranch_scc1 .LBB0_711
	s_setprio 0
	s_lshl_b32 s13, s14, 7
	s_add_i32 s15, s13, 0xffffef00
	s_cmp_lt_i32 s14, 34
	s_mov_b32 s14, 0x4100000
	s_cselect_b32 s18, s14, 0xcb20000
	s_movk_i32 s0, 0x1200
	s_cselect_b32 s15, s13, s15
	s_cselect_b32 s14, 0x1100, s0
	v_lshl_add_u32 v2, s12, 8, v138
	s_add_u32 s12, s10, s18
	v_or_b32_e32 v0, s15, v139
	s_addc_u32 s13, s11, 0
	s_lshl_b32 s18, s14, 4
	v_ashrrev_i32_e32 v1, 31, v0
	v_lshlrev_b64 v[0:1], 1, v[0:1]
	v_bfe_u32 v136, v178, 4, 1
	v_mul_u32_u24_e32 v136, 24, v136
	v_add_u32_e32 v0, v0, v136
	v_bfe_u32 v136, v178, 3, 1
	v_lshlrev_b32_e32 v136, 6, v136
	v_add_u32_e32 v0, v0, v136
	v_and_b32_e32 v2, 0xfffffff7, v2
	v_mad_i64_i32 v[132:133], s[26:27], s14, v2, 0
	v_lshl_add_u64 v[132:133], v[132:133], 1, s[12:13]
	v_lshl_add_u64 v[132:133], v[132:133], 0, v[0:1]
	v_lshl_add_u64 v[134:135], v[132:133], 0, s[18:19]
	v_cvt_pk_bf16_f32 v144, v128, v129
	v_cvt_pk_bf16_f32 v146, v124, v125
	v_cvt_pk_bf16_f32 v145, v130, v131
	v_cvt_pk_bf16_f32 v147, v126, v127
	v_cvt_pk_bf16_f32 v148, v120, v121
	v_cvt_pk_bf16_f32 v150, v116, v117
	v_cvt_pk_bf16_f32 v149, v122, v123
	v_cvt_pk_bf16_f32 v151, v118, v119
	v_permlane16_swap_b32_e32 v144, v146
	v_permlane16_swap_b32_e32 v145, v147
	v_permlane16_swap_b32_e32 v148, v150
	v_permlane16_swap_b32_e32 v149, v151
	v_mov_b32_e32 v152, v144
	v_mov_b32_e32 v153, v145
	v_mov_b32_e32 v154, v146
	v_mov_b32_e32 v155, v147
	v_mov_b32_dpp v144, v148 row_ror:8 row_mask:0xf bank_mask:0xc
	v_mov_b32_dpp v145, v149 row_ror:8 row_mask:0xf bank_mask:0xc
	v_mov_b32_dpp v146, v150 row_ror:8 row_mask:0xf bank_mask:0xc
	v_mov_b32_dpp v147, v151 row_ror:8 row_mask:0xf bank_mask:0xc
	v_mov_b32_dpp v148, v152 row_ror:8 row_mask:0xf bank_mask:0x3
	v_mov_b32_dpp v149, v153 row_ror:8 row_mask:0xf bank_mask:0x3
	v_mov_b32_dpp v150, v154 row_ror:8 row_mask:0xf bank_mask:0x3
	v_mov_b32_dpp v151, v155 row_ror:8 row_mask:0xf bank_mask:0x3
	global_store_dwordx4 v[132:133], v[144:147], off nt
	global_store_dwordx4 v[134:135], v[148:151], off nt
	v_or_b32_e32 v172, 0x10, v2
	v_mad_i64_i32 v[168:169], s[26:27], s14, v172, 0
	v_lshl_add_u64 v[168:169], v[168:169], 1, s[12:13]
	v_lshl_add_u64 v[168:169], v[168:169], 0, v[0:1]
	v_lshl_add_u64 v[170:171], v[168:169], 0, s[18:19]
	v_cvt_pk_bf16_f32 v156, v112, v113
	v_cvt_pk_bf16_f32 v158, v108, v109
	v_cvt_pk_bf16_f32 v157, v114, v115
	v_cvt_pk_bf16_f32 v159, v110, v111
	v_cvt_pk_bf16_f32 v160, v104, v105
	v_cvt_pk_bf16_f32 v162, v100, v101
	v_cvt_pk_bf16_f32 v161, v106, v107
	v_cvt_pk_bf16_f32 v163, v102, v103
	v_permlane16_swap_b32_e32 v156, v158
	v_permlane16_swap_b32_e32 v157, v159
	v_permlane16_swap_b32_e32 v160, v162
	v_permlane16_swap_b32_e32 v161, v163
	v_mov_b32_e32 v164, v156
	v_mov_b32_e32 v165, v157
	v_mov_b32_e32 v166, v158
	v_mov_b32_e32 v167, v159
	v_mov_b32_dpp v156, v160 row_ror:8 row_mask:0xf bank_mask:0xc
	v_mov_b32_dpp v157, v161 row_ror:8 row_mask:0xf bank_mask:0xc
	v_mov_b32_dpp v158, v162 row_ror:8 row_mask:0xf bank_mask:0xc
	v_mov_b32_dpp v159, v163 row_ror:8 row_mask:0xf bank_mask:0xc
	v_mov_b32_dpp v160, v164 row_ror:8 row_mask:0xf bank_mask:0x3
	v_mov_b32_dpp v161, v165 row_ror:8 row_mask:0xf bank_mask:0x3
	v_mov_b32_dpp v162, v166 row_ror:8 row_mask:0xf bank_mask:0x3
	v_mov_b32_dpp v163, v167 row_ror:8 row_mask:0xf bank_mask:0x3
	global_store_dwordx4 v[168:169], v[156:159], off nt
	global_store_dwordx4 v[170:171], v[160:163], off nt
	v_or_b32_e32 v172, 0x20, v2
	v_mad_i64_i32 v[132:133], s[26:27], s14, v172, 0
	v_lshl_add_u64 v[132:133], v[132:133], 1, s[12:13]
	v_lshl_add_u64 v[132:133], v[132:133], 0, v[0:1]
	v_lshl_add_u64 v[134:135], v[132:133], 0, s[18:19]
	v_cvt_pk_bf16_f32 v144, v96, v97
	v_cvt_pk_bf16_f32 v146, v92, v93
	v_cvt_pk_bf16_f32 v145, v98, v99
	v_cvt_pk_bf16_f32 v147, v94, v95
; __device__ __forceinline__ unsigned pack2(float a, float b) { return (unsigned)f2bf(a) | ((unsigned)f2bf(b) << 16); }
; __device__ __forceinline__ void phase_gemm_in(const Params& p, char* smem) {
;     ...
; #pragma unroll
;     for (int i = 0; i < 8; ++i) {
;       const int m = mt * 256 + wm * 128 + i * 16 + (lane & 15);
; #pragma unroll
;       for (int j = 0; j < 4; ++j) {
;         const int n = ncol0 + wn * 64 + j * 16 + (lane >> 4) * 4;
;         uint2 o;
;         o.x = pack2(acc[i][j][0], acc[i][j][1]);
;         o.y = pack2(acc[i][j][2], acc[i][j][3]);
;         *(uint2*)(dst + (size_t)m * ldd + n) = o;
;       }
;     }
	v_cvt_pk_bf16_f32 v148, v88, v89
	v_cvt_pk_bf16_f32 v150, v84, v85
	v_cvt_pk_bf16_f32 v149, v90, v91
	v_cvt_pk_bf16_f32 v151, v86, v87
	v_permlane16_swap_b32_e32 v144, v146
	v_permlane16_swap_b32_e32 v145, v147
	v_permlane16_swap_b32_e32 v148, v150
	v_permlane16_swap_b32_e32 v149, v151
	v_mov_b32_e32 v152, v144
	v_mov_b32_e32 v153, v145
	v_mov_b32_e32 v154, v146
	v_mov_b32_e32 v155, v147
	v_mov_b32_dpp v144, v148 row_ror:8 row_mask:0xf bank_mask:0xc
	v_mov_b32_dpp v145, v149 row_ror:8 row_mask:0xf bank_mask:0xc
	v_mov_b32_dpp v146, v150 row_ror:8 row_mask:0xf bank_mask:0xc
	v_mov_b32_dpp v147, v151 row_ror:8 row_mask:0xf bank_mask:0xc
	v_mov_b32_dpp v148, v152 row_ror:8 row_mask:0xf bank_mask:0x3
	v_mov_b32_dpp v149, v153 row_ror:8 row_mask:0xf bank_mask:0x3
	v_mov_b32_dpp v150, v154 row_ror:8 row_mask:0xf bank_mask:0x3
	v_mov_b32_dpp v151, v155 row_ror:8 row_mask:0xf bank_mask:0x3
	global_store_dwordx4 v[132:133], v[144:147], off nt
	global_store_dwordx4 v[134:135], v[148:151], off nt
	v_or_b32_e32 v172, 0x30, v2
	v_mad_i64_i32 v[168:169], s[26:27], s14, v172, 0
	v_lshl_add_u64 v[168:169], v[168:169], 1, s[12:13]
	v_lshl_add_u64 v[168:169], v[168:169], 0, v[0:1]
	v_lshl_add_u64 v[170:171], v[168:169], 0, s[18:19]
	v_cvt_pk_bf16_f32 v156, v80, v81
	v_cvt_pk_bf16_f32 v158, v76, v77
	v_cvt_pk_bf16_f32 v157, v82, v83
	v_cvt_pk_bf16_f32 v159, v78, v79
	v_cvt_pk_bf16_f32 v160, v72, v73
	v_cvt_pk_bf16_f32 v162, v68, v69
	v_cvt_pk_bf16_f32 v161, v74, v75
	v_cvt_pk_bf16_f32 v163, v70, v71
	v_permlane16_swap_b32_e32 v156, v158
	v_permlane16_swap_b32_e32 v157, v159
	v_permlane16_swap_b32_e32 v160, v162
	v_permlane16_swap_b32_e32 v161, v163
	v_mov_b32_e32 v164, v156
	v_mov_b32_e32 v165, v157
	v_mov_b32_e32 v166, v158
	v_mov_b32_e32 v167, v159
	v_mov_b32_dpp v156, v160 row_ror:8 row_mask:0xf bank_mask:0xc
	v_mov_b32_dpp v157, v161 row_ror:8 row_mask:0xf bank_mask:0xc
	v_mov_b32_dpp v158, v162 row_ror:8 row_mask:0xf bank_mask:0xc
	v_mov_b32_dpp v159, v163 row_ror:8 row_mask:0xf bank_mask:0xc
	v_mov_b32_dpp v160, v164 row_ror:8 row_mask:0xf bank_mask:0x3
	v_mov_b32_dpp v161, v165 row_ror:8 row_mask:0xf bank_mask:0x3
	v_mov_b32_dpp v162, v166 row_ror:8 row_mask:0xf bank_mask:0x3
	v_mov_b32_dpp v163, v167 row_ror:8 row_mask:0xf bank_mask:0x3
	global_store_dwordx4 v[168:169], v[156:159], off nt
	global_store_dwordx4 v[170:171], v[160:163], off nt
	v_or_b32_e32 v172, 0x40, v2
	v_mad_i64_i32 v[132:133], s[26:27], s14, v172, 0
	v_lshl_add_u64 v[132:133], v[132:133], 1, s[12:13]
	v_lshl_add_u64 v[132:133], v[132:133], 0, v[0:1]
	v_lshl_add_u64 v[134:135], v[132:133], 0, s[18:19]
	v_cvt_pk_bf16_f32 v144, v64, v65
	v_cvt_pk_bf16_f32 v146, v60, v61
	v_cvt_pk_bf16_f32 v145, v66, v67
	v_cvt_pk_bf16_f32 v147, v62, v63
	v_cvt_pk_bf16_f32 v148, v56, v57
	v_cvt_pk_bf16_f32 v150, v52, v53
	v_cvt_pk_bf16_f32 v149, v58, v59
	v_cvt_pk_bf16_f32 v151, v54, v55
	v_permlane16_swap_b32_e32 v144, v146
	v_permlane16_swap_b32_e32 v145, v147
	v_permlane16_swap_b32_e32 v148, v150
	v_permlane16_swap_b32_e32 v149, v151
	v_mov_b32_e32 v152, v144
	v_mov_b32_e32 v153, v145
	v_mov_b32_e32 v154, v146
	v_mov_b32_e32 v155, v147
	v_mov_b32_dpp v144, v148 row_ror:8 row_mask:0xf bank_mask:0xc
	v_mov_b32_dpp v145, v149 row_ror:8 row_mask:0xf bank_mask:0xc
	v_mov_b32_dpp v146, v150 row_ror:8 row_mask:0xf bank_mask:0xc
	v_mov_b32_dpp v147, v151 row_ror:8 row_mask:0xf bank_mask:0xc
	v_mov_b32_dpp v148, v152 row_ror:8 row_mask:0xf bank_mask:0x3
	v_mov_b32_dpp v149, v153 row_ror:8 row_mask:0xf bank_mask:0x3
	v_mov_b32_dpp v150, v154 row_ror:8 row_mask:0xf bank_mask:0x3
	v_mov_b32_dpp v151, v155 row_ror:8 row_mask:0xf bank_mask:0x3
	global_store_dwordx4 v[132:133], v[144:147], off nt
	global_store_dwordx4 v[134:135], v[148:151], off nt
	v_or_b32_e32 v172, 0x50, v2
	v_mad_i64_i32 v[168:169], s[26:27], s14, v172, 0
	v_lshl_add_u64 v[168:169], v[168:169], 1, s[12:13]
	v_lshl_add_u64 v[168:169], v[168:169], 0, v[0:1]
	v_lshl_add_u64 v[170:171], v[168:169], 0, s[18:19]
; __device__ __forceinline__ unsigned pack2(float a, float b) { return (unsigned)f2bf(a) | ((unsigned)f2bf(b) << 16); }
; __device__ __forceinline__ void phase_gemm_in(const Params& p, char* smem) {
;     ...
; #pragma unroll
;     for (int i = 0; i < 8; ++i) {
;       const int m = mt * 256 + wm * 128 + i * 16 + (lane & 15);
; #pragma unroll
;       for (int j = 0; j < 4; ++j) {
;         const int n = ncol0 + wn * 64 + j * 16 + (lane >> 4) * 4;
;         uint2 o;
;         o.x = pack2(acc[i][j][0], acc[i][j][1]);
;         o.y = pack2(acc[i][j][2], acc[i][j][3]);
;         *(uint2*)(dst + (size_t)m * ldd + n) = o;
;       }
;     }
	v_cvt_pk_bf16_f32 v156, v48, v49
	v_cvt_pk_bf16_f32 v158, v44, v45
	v_cvt_pk_bf16_f32 v157, v50, v51
	v_cvt_pk_bf16_f32 v159, v46, v47
	v_cvt_pk_bf16_f32 v160, v40, v41
	v_cvt_pk_bf16_f32 v162, v36, v37
	v_cvt_pk_bf16_f32 v161, v42, v43
	v_cvt_pk_bf16_f32 v163, v38, v39
	v_permlane16_swap_b32_e32 v156, v158
	v_permlane16_swap_b32_e32 v157, v159
	v_permlane16_swap_b32_e32 v160, v162
	v_permlane16_swap_b32_e32 v161, v163
	v_mov_b32_e32 v164, v156
	v_mov_b32_e32 v165, v157
	v_mov_b32_e32 v166, v158
	v_mov_b32_e32 v167, v159
	v_mov_b32_dpp v156, v160 row_ror:8 row_mask:0xf bank_mask:0xc
	v_mov_b32_dpp v157, v161 row_ror:8 row_mask:0xf bank_mask:0xc
	v_mov_b32_dpp v158, v162 row_ror:8 row_mask:0xf bank_mask:0xc
	v_mov_b32_dpp v159, v163 row_ror:8 row_mask:0xf bank_mask:0xc
	v_mov_b32_dpp v160, v164 row_ror:8 row_mask:0xf bank_mask:0x3
	v_mov_b32_dpp v161, v165 row_ror:8 row_mask:0xf bank_mask:0x3
	v_mov_b32_dpp v162, v166 row_ror:8 row_mask:0xf bank_mask:0x3
	v_mov_b32_dpp v163, v167 row_ror:8 row_mask:0xf bank_mask:0x3
	global_store_dwordx4 v[168:169], v[156:159], off nt
	global_store_dwordx4 v[170:171], v[160:163], off nt
	v_or_b32_e32 v172, 0x60, v2
	v_mad_i64_i32 v[132:133], s[26:27], s14, v172, 0
	v_lshl_add_u64 v[132:133], v[132:133], 1, s[12:13]
	v_lshl_add_u64 v[132:133], v[132:133], 0, v[0:1]
	v_lshl_add_u64 v[134:135], v[132:133], 0, s[18:19]
	v_cvt_pk_bf16_f32 v144, v32, v33
	v_cvt_pk_bf16_f32 v146, v24, v25
	v_cvt_pk_bf16_f32 v145, v34, v35
	v_cvt_pk_bf16_f32 v147, v26, v27
	v_cvt_pk_bf16_f32 v148, v20, v21
	v_cvt_pk_bf16_f32 v150, v16, v17
	v_cvt_pk_bf16_f32 v149, v22, v23
	v_cvt_pk_bf16_f32 v151, v18, v19
	v_permlane16_swap_b32_e32 v144, v146
	v_permlane16_swap_b32_e32 v145, v147
	v_permlane16_swap_b32_e32 v148, v150
	v_permlane16_swap_b32_e32 v149, v151
	v_mov_b32_e32 v152, v144
	v_mov_b32_e32 v153, v145
	v_mov_b32_e32 v154, v146
	v_mov_b32_e32 v155, v147
	v_mov_b32_dpp v144, v148 row_ror:8 row_mask:0xf bank_mask:0xc
	v_mov_b32_dpp v145, v149 row_ror:8 row_mask:0xf bank_mask:0xc
	v_mov_b32_dpp v146, v150 row_ror:8 row_mask:0xf bank_mask:0xc
	v_mov_b32_dpp v147, v151 row_ror:8 row_mask:0xf bank_mask:0xc
	v_mov_b32_dpp v148, v152 row_ror:8 row_mask:0xf bank_mask:0x3
	v_mov_b32_dpp v149, v153 row_ror:8 row_mask:0xf bank_mask:0x3
	v_mov_b32_dpp v150, v154 row_ror:8 row_mask:0xf bank_mask:0x3
	v_mov_b32_dpp v151, v155 row_ror:8 row_mask:0xf bank_mask:0x3
	global_store_dwordx4 v[132:133], v[144:147], off nt
	global_store_dwordx4 v[134:135], v[148:151], off nt
	v_or_b32_e32 v172, 0x70, v2
	v_mad_i64_i32 v[168:169], s[26:27], s14, v172, 0
	v_lshl_add_u64 v[168:169], v[168:169], 1, s[12:13]
	v_lshl_add_u64 v[168:169], v[168:169], 0, v[0:1]
	v_lshl_add_u64 v[170:171], v[168:169], 0, s[18:19]
	v_cvt_pk_bf16_f32 v156, v12, v13
	v_cvt_pk_bf16_f32 v158, v8, v9
	v_cvt_pk_bf16_f32 v157, v14, v15
	v_cvt_pk_bf16_f32 v159, v10, v11
	v_cvt_pk_bf16_f32 v160, v4, v5
	v_cvt_pk_bf16_f32 v162, v28, v29
	v_cvt_pk_bf16_f32 v161, v6, v7
	v_cvt_pk_bf16_f32 v163, v30, v31
	v_permlane16_swap_b32_e32 v156, v158
	v_permlane16_swap_b32_e32 v157, v159
	v_permlane16_swap_b32_e32 v160, v162
	v_permlane16_swap_b32_e32 v161, v163
	v_mov_b32_e32 v164, v156
	v_mov_b32_e32 v165, v157
	v_mov_b32_e32 v166, v158
	v_mov_b32_e32 v167, v159
	v_mov_b32_dpp v156, v160 row_ror:8 row_mask:0xf bank_mask:0xc
	v_mov_b32_dpp v157, v161 row_ror:8 row_mask:0xf bank_mask:0xc
	v_mov_b32_dpp v158, v162 row_ror:8 row_mask:0xf bank_mask:0xc
	v_mov_b32_dpp v159, v163 row_ror:8 row_mask:0xf bank_mask:0xc
	v_mov_b32_dpp v160, v164 row_ror:8 row_mask:0xf bank_mask:0x3
	v_mov_b32_dpp v161, v165 row_ror:8 row_mask:0xf bank_mask:0x3
	v_mov_b32_dpp v162, v166 row_ror:8 row_mask:0xf bank_mask:0x3
	v_mov_b32_dpp v163, v167 row_ror:8 row_mask:0xf bank_mask:0x3
	global_store_dwordx4 v[168:169], v[156:159], off nt
	global_store_dwordx4 v[170:171], v[160:163], off nt
	s_add_i32 s23, s23, 1
	s_cmp_eq_u32 s23, s17
	s_cselect_b64 s[12:13], -1, 0
	s_mov_b32 s31, 0x18000
	s_branch .LBB0_708
